# select search: per-pass trims (no accumulator zeroing, direct key for the transformed probe)
# speedup vs baseline: 1.0026x; 1.0026x over previous
; __device__ __forceinline__ int count_ge(const unsigned (&u)[64], unsigned cand, int nblk) {
;     int c0 = 0, c1 = 0;
;     const unsigned ts = __builtin_amdgcn_readfirstlane(cand);
; #pragma unroll
;     for (int B = 0; B < 2; ++B) {
;         if (B < nblk) {
; #pragma unroll
;             for (int i = 0; i < 32; i += 4) CNT4(c0, c1, ts, u[B * 32 + i], u[B * 32 + i + 1], u[B * 32 + i + 2], u[B * 32 + i + 3]);
;         }
;     }
;     return wave_isum(c0 + c1);
; }
.Lsqa_count:
	v_cmp_le_u32_e64 s[4:5], s14, v138
	v_cmp_le_u32_e64 s[6:7], s14, v140
	v_cmp_le_u32_e64 s[10:11], s14, v139
	v_cmp_le_u32_e64 s[26:27], s14, v141
	v_addc_co_u32_e64 v0, s[28:29], 0, 0, s[4:5]
	v_addc_co_u32_e64 v34, s[30:31], 0, 0, s[6:7]
	v_addc_co_u32_e64 v0, s[28:29], 0, v0, s[10:11]
	v_addc_co_u32_e64 v34, s[30:31], 0, v34, s[26:27]
	v_cmp_le_u32_e64 s[4:5], s14, v142
	v_cmp_le_u32_e64 s[6:7], s14, v146
	v_cmp_le_u32_e64 s[10:11], s14, v143
	v_cmp_le_u32_e64 s[26:27], s14, v147
	v_addc_co_u32_e64 v0, s[28:29], 0, v0, s[4:5]
	v_addc_co_u32_e64 v34, s[30:31], 0, v34, s[6:7]
	v_addc_co_u32_e64 v0, s[28:29], 0, v0, s[10:11]
	v_addc_co_u32_e64 v34, s[30:31], 0, v34, s[26:27]
	s_cmp_eq_u32 s32, 1
	s_cbranch_scc1 .Lsqa_red
	v_cmp_le_u32_e64 s[4:5], s14, v144
	v_cmp_le_u32_e64 s[6:7], s14, v148
	v_cmp_le_u32_e64 s[10:11], s14, v145
	v_cmp_le_u32_e64 s[26:27], s14, v149
	v_addc_co_u32_e64 v0, s[28:29], 0, v0, s[4:5]
	v_addc_co_u32_e64 v34, s[30:31], 0, v34, s[6:7]
	v_addc_co_u32_e64 v0, s[28:29], 0, v0, s[10:11]
	v_addc_co_u32_e64 v34, s[30:31], 0, v34, s[26:27]
	v_cmp_le_u32_e64 s[4:5], s14, v150
	v_cmp_le_u32_e64 s[6:7], s14, v152
	v_cmp_le_u32_e64 s[10:11], s14, v151
	v_cmp_le_u32_e64 s[26:27], s14, v154
	v_addc_co_u32_e64 v0, s[28:29], 0, v0, s[4:5]
	v_addc_co_u32_e64 v34, s[30:31], 0, v34, s[6:7]
	v_addc_co_u32_e64 v0, s[28:29], 0, v0, s[10:11]
	v_addc_co_u32_e64 v34, s[30:31], 0, v34, s[26:27]
	s_cmp_eq_u32 s32, 2
	s_cbranch_scc1 .Lsqa_red
	v_cmp_le_u32_e64 s[4:5], s14, v153
	v_cmp_le_u32_e64 s[6:7], s14, v156
	v_cmp_le_u32_e64 s[10:11], s14, v155
	v_cmp_le_u32_e64 s[26:27], s14, v157
	v_addc_co_u32_e64 v0, s[28:29], 0, v0, s[4:5]
	v_addc_co_u32_e64 v34, s[30:31], 0, v34, s[6:7]
	v_addc_co_u32_e64 v0, s[28:29], 0, v0, s[10:11]
	v_addc_co_u32_e64 v34, s[30:31], 0, v34, s[26:27]
	v_cmp_le_u32_e64 s[4:5], s14, v158
	v_cmp_le_u32_e64 s[6:7], s14, v160
	v_cmp_le_u32_e64 s[10:11], s14, v159
	v_cmp_le_u32_e64 s[26:27], s14, v161
	v_addc_co_u32_e64 v0, s[28:29], 0, v0, s[4:5]
	v_addc_co_u32_e64 v34, s[30:31], 0, v34, s[6:7]
	v_addc_co_u32_e64 v0, s[28:29], 0, v0, s[10:11]
	v_addc_co_u32_e64 v34, s[30:31], 0, v34, s[26:27]
	v_cmp_le_u32_e64 s[4:5], s14, v167
	v_cmp_le_u32_e64 s[6:7], s14, v169
	v_cmp_le_u32_e64 s[10:11], s14, v168
	v_cmp_le_u32_e64 s[26:27], s14, v170
	v_addc_co_u32_e64 v0, s[28:29], 0, v0, s[4:5]
	v_addc_co_u32_e64 v34, s[30:31], 0, v34, s[6:7]
	v_addc_co_u32_e64 v0, s[28:29], 0, v0, s[10:11]
	v_addc_co_u32_e64 v34, s[30:31], 0, v34, s[26:27]
	v_cmp_le_u32_e64 s[4:5], s14, v173
	v_cmp_le_u32_e64 s[6:7], s14, v174
	v_cmp_le_u32_e64 s[10:11], s14, v175
	v_cmp_le_u32_e64 s[26:27], s14, v176
	v_addc_co_u32_e64 v0, s[28:29], 0, v0, s[4:5]
	v_addc_co_u32_e64 v34, s[30:31], 0, v34, s[6:7]
	v_addc_co_u32_e64 v0, s[28:29], 0, v0, s[10:11]
	v_addc_co_u32_e64 v34, s[30:31], 0, v34, s[26:27]
	s_cmp_eq_u32 s32, 3
	s_cbranch_scc1 .Lsqa_red
	v_cmp_le_u32_e64 s[4:5], s14, v76
	v_cmp_le_u32_e64 s[6:7], s14, v78
	v_cmp_le_u32_e64 s[10:11], s14, v77
	v_cmp_le_u32_e64 s[26:27], s14, v79
	v_addc_co_u32_e64 v0, s[28:29], 0, v0, s[4:5]
	v_addc_co_u32_e64 v34, s[30:31], 0, v34, s[6:7]
	v_addc_co_u32_e64 v0, s[28:29], 0, v0, s[10:11]
	v_addc_co_u32_e64 v34, s[30:31], 0, v34, s[26:27]
	v_cmp_le_u32_e64 s[4:5], s14, v80
	v_cmp_le_u32_e64 s[6:7], s14, v84
	v_cmp_le_u32_e64 s[10:11], s14, v81
	v_cmp_le_u32_e64 s[26:27], s14, v85
	v_addc_co_u32_e64 v0, s[28:29], 0, v0, s[4:5]
	v_addc_co_u32_e64 v34, s[30:31], 0, v34, s[6:7]
	v_addc_co_u32_e64 v0, s[28:29], 0, v0, s[10:11]
	v_addc_co_u32_e64 v34, s[30:31], 0, v34, s[26:27]
	s_cmp_eq_u32 s32, 4
	s_cbranch_scc1 .Lsqa_red
	v_cmp_le_u32_e64 s[4:5], s14, v82
	v_cmp_le_u32_e64 s[6:7], s14, v86
	v_cmp_le_u32_e64 s[10:11], s14, v83
	v_cmp_le_u32_e64 s[26:27], s14, v87
	v_addc_co_u32_e64 v0, s[28:29], 0, v0, s[4:5]
	v_addc_co_u32_e64 v34, s[30:31], 0, v34, s[6:7]
	v_addc_co_u32_e64 v0, s[28:29], 0, v0, s[10:11]
	v_addc_co_u32_e64 v34, s[30:31], 0, v34, s[26:27]
	v_cmp_le_u32_e64 s[4:5], s14, v89
	v_cmp_le_u32_e64 s[6:7], s14, v91
	v_cmp_le_u32_e64 s[10:11], s14, v90
	v_cmp_le_u32_e64 s[26:27], s14, v93
	v_addc_co_u32_e64 v0, s[28:29], 0, v0, s[4:5]
	v_addc_co_u32_e64 v34, s[30:31], 0, v34, s[6:7]
	v_addc_co_u32_e64 v0, s[28:29], 0, v0, s[10:11]
	v_addc_co_u32_e64 v34, s[30:31], 0, v34, s[26:27]
	s_cmp_eq_u32 s32, 5
	s_cbranch_scc1 .Lsqa_red
	v_cmp_le_u32_e64 s[4:5], s14, v92
	v_cmp_le_u32_e64 s[6:7], s14, v95
	v_cmp_le_u32_e64 s[10:11], s14, v94
	v_cmp_le_u32_e64 s[26:27], s14, v96
	v_addc_co_u32_e64 v0, s[28:29], 0, v0, s[4:5]
	v_addc_co_u32_e64 v34, s[30:31], 0, v34, s[6:7]
	v_addc_co_u32_e64 v0, s[28:29], 0, v0, s[10:11]
	v_addc_co_u32_e64 v34, s[30:31], 0, v34, s[26:27]
	v_cmp_le_u32_e64 s[4:5], s14, v97
	v_cmp_le_u32_e64 s[6:7], s14, v172
	v_cmp_le_u32_e64 s[10:11], s14, v171
	v_cmp_le_u32_e64 s[26:27], s14, v178
	v_addc_co_u32_e64 v0, s[28:29], 0, v0, s[4:5]
	v_addc_co_u32_e64 v34, s[30:31], 0, v34, s[6:7]
	v_addc_co_u32_e64 v0, s[28:29], 0, v0, s[10:11]
	v_addc_co_u32_e64 v34, s[30:31], 0, v34, s[26:27]
	v_cmp_le_u32_e64 s[4:5], s14, v180
	v_cmp_le_u32_e64 s[6:7], s14, v183
	v_cmp_le_u32_e64 s[10:11], s14, v182
	v_cmp_le_u32_e64 s[26:27], s14, v184
	v_addc_co_u32_e64 v0, s[28:29], 0, v0, s[4:5]
	v_addc_co_u32_e64 v34, s[30:31], 0, v34, s[6:7]
	v_addc_co_u32_e64 v0, s[28:29], 0, v0, s[10:11]
	v_addc_co_u32_e64 v34, s[30:31], 0, v34, s[26:27]
	v_cmp_le_u32_e64 s[4:5], s14, v186
	v_cmp_le_u32_e64 s[6:7], s14, v187
	v_cmp_le_u32_e64 s[10:11], s14, v188
	v_cmp_le_u32_e64 s[26:27], s14, v189
	v_addc_co_u32_e64 v0, s[28:29], 0, v0, s[4:5]
	v_addc_co_u32_e64 v34, s[30:31], 0, v34, s[6:7]
	v_addc_co_u32_e64 v0, s[28:29], 0, v0, s[10:11]
	v_addc_co_u32_e64 v34, s[30:31], 0, v34, s[26:27]

; __device__ __forceinline__ float keyval(unsigned k) { return __uint_as_float((k & 0x80000000u) ? (k ^ 0x80000000u) : ~k); }
; __device__ __forceinline__ unsigned valkey(float f) { const unsigned b = __float_as_uint(f); return b ^ ((unsigned)((int)b >> 31) | 0x80000000u); }
; __device__ __forceinline__ void select_query(const unsigned (&u)[64], unsigned vmax, int q, int b, int lane, unsigned* MASKb) {
;     ...
;         while (!done) {
;             if (hi - lo <= 1u) { T = lo; exact = false; break; }
;             const float vlo = keyval(lo), vhi = keyval(hi);
;             const float frac = (it >= 9 && (it & 1)) ? 0.5f : Llo * __builtin_amdgcn_rcpf(Llo + Lhi);
;             unsigned mid = valkey(vlo + frac * (vhi - vlo));
;             if (mid <= lo) mid = lo + 1u;
;             if (mid >= hi) mid = hi - 1u;
;             mid = __builtin_amdgcn_readfirstlane(mid);
.Lsqa_next:
	s_sub_u32 s26, s12, s13
	s_cmp_lt_u32 s26, 2
	s_cbranch_scc1 .Lsqa_collapse
	s_cmp_eq_u32 s101, 0
	s_cbranch_scc1 .Lsqa_lin
	s_cmp_lt_i32 s22, 9
	s_cbranch_scc0 .Lsqa_lin
	v_add_f32_e32 v191, v35, v36
	v_sub_f32_e32 v34, v193, v192
	v_rcp_f32_e32 v191, v191
	s_nop 0
	v_mul_f32_e32 v191, v35, v191
	v_fma_f32 v88, v191, v34, v192
	v_log_f32_e32 v0, v88
	s_nop 0
	v_mul_f32_e32 v0, 0x3f2aaaab, v0
	v_exp_f32_e32 v191, v0
	s_nop 0
	v_readfirstlane_b32 s14, v191
	s_bitset1_b32 s14, 31
	s_branch .Lsqa_clamp

; __device__ __forceinline__ void select_query(const unsigned (&u)[64], unsigned vmax, int q, int b, int lane, unsigned* MASKb) {
;     ...
;             if (mid <= lo) mid = lo + 1u;
;             if (mid >= hi) mid = hi - 1u;
;             mid = __builtin_amdgcn_readfirstlane(mid);
.Lsqa_clamp:
	s_add_i32 s26, s13, 1
	s_max_u32 s14, s14, s26
	s_add_i32 s26, s12, -1
	s_min_u32 s14, s14, s26
	s_branch .Lsqa_count

; __device__ __forceinline__ int count_ge(const unsigned (&u)[64], unsigned cand, int nblk) {
;     int c0 = 0, c1 = 0;
;     const unsigned ts = __builtin_amdgcn_readfirstlane(cand);
; #pragma unroll
;     for (int B = 0; B < 2; ++B) {
;         if (B < nblk) {
; #pragma unroll
;             for (int i = 0; i < 32; i += 4) CNT4(c0, c1, ts, u[B * 32 + i], u[B * 32 + i + 1], u[B * 32 + i + 2], u[B * 32 + i + 3]);
;         }
;     }
;     return wave_isum(c0 + c1);
; }
.Lsqb_count:
	v_cmp_le_u32_e64 s[4:5], s14, v98
	v_cmp_le_u32_e64 s[6:7], s14, v107
	v_cmp_le_u32_e64 s[10:11], s14, v99
	v_cmp_le_u32_e64 s[26:27], s14, v108
	v_addc_co_u32_e64 v138, s[28:29], 0, 0, s[4:5]
	v_addc_co_u32_e64 v140, s[30:31], 0, 0, s[6:7]
	v_addc_co_u32_e64 v138, s[28:29], 0, v138, s[10:11]
	v_addc_co_u32_e64 v140, s[30:31], 0, v140, s[26:27]
	v_cmp_le_u32_e64 s[4:5], s14, v109
	v_cmp_le_u32_e64 s[6:7], s14, v113
	v_cmp_le_u32_e64 s[10:11], s14, v110
	v_cmp_le_u32_e64 s[26:27], s14, v114
	v_addc_co_u32_e64 v138, s[28:29], 0, v138, s[4:5]
	v_addc_co_u32_e64 v140, s[30:31], 0, v140, s[6:7]
	v_addc_co_u32_e64 v138, s[28:29], 0, v138, s[10:11]
	v_addc_co_u32_e64 v140, s[30:31], 0, v140, s[26:27]
	s_cmp_eq_u32 s32, 1
	s_cbranch_scc1 .Lsqb_red
	v_cmp_le_u32_e64 s[4:5], s14, v111
	v_cmp_le_u32_e64 s[6:7], s14, v115
	v_cmp_le_u32_e64 s[10:11], s14, v112
	v_cmp_le_u32_e64 s[26:27], s14, v116
	v_addc_co_u32_e64 v138, s[28:29], 0, v138, s[4:5]
	v_addc_co_u32_e64 v140, s[30:31], 0, v140, s[6:7]
	v_addc_co_u32_e64 v138, s[28:29], 0, v138, s[10:11]
	v_addc_co_u32_e64 v140, s[30:31], 0, v140, s[26:27]
	v_cmp_le_u32_e64 s[4:5], s14, v117
	v_cmp_le_u32_e64 s[6:7], s14, v119
	v_cmp_le_u32_e64 s[10:11], s14, v118
	v_cmp_le_u32_e64 s[26:27], s14, v121
	v_addc_co_u32_e64 v138, s[28:29], 0, v138, s[4:5]
	v_addc_co_u32_e64 v140, s[30:31], 0, v140, s[6:7]
	v_addc_co_u32_e64 v138, s[28:29], 0, v138, s[10:11]
	v_addc_co_u32_e64 v140, s[30:31], 0, v140, s[26:27]
	s_cmp_eq_u32 s32, 2
	s_cbranch_scc1 .Lsqb_red
	v_cmp_le_u32_e64 s[4:5], s14, v120
	v_cmp_le_u32_e64 s[6:7], s14, v123
	v_cmp_le_u32_e64 s[10:11], s14, v122
	v_cmp_le_u32_e64 s[26:27], s14, v124
	v_addc_co_u32_e64 v138, s[28:29], 0, v138, s[4:5]
	v_addc_co_u32_e64 v140, s[30:31], 0, v140, s[6:7]
	v_addc_co_u32_e64 v138, s[28:29], 0, v138, s[10:11]
	v_addc_co_u32_e64 v140, s[30:31], 0, v140, s[26:27]
	v_cmp_le_u32_e64 s[4:5], s14, v125
	v_cmp_le_u32_e64 s[6:7], s14, v127
	v_cmp_le_u32_e64 s[10:11], s14, v126
	v_cmp_le_u32_e64 s[26:27], s14, v128
	v_addc_co_u32_e64 v138, s[28:29], 0, v138, s[4:5]
	v_addc_co_u32_e64 v140, s[30:31], 0, v140, s[6:7]
	v_addc_co_u32_e64 v138, s[28:29], 0, v138, s[10:11]
	v_addc_co_u32_e64 v140, s[30:31], 0, v140, s[26:27]
	v_cmp_le_u32_e64 s[4:5], s14, v129
	v_cmp_le_u32_e64 s[6:7], s14, v131
	v_cmp_le_u32_e64 s[10:11], s14, v130
	v_cmp_le_u32_e64 s[26:27], s14, v132
	v_addc_co_u32_e64 v138, s[28:29], 0, v138, s[4:5]
	v_addc_co_u32_e64 v140, s[30:31], 0, v140, s[6:7]
	v_addc_co_u32_e64 v138, s[28:29], 0, v138, s[10:11]
	v_addc_co_u32_e64 v140, s[30:31], 0, v140, s[26:27]
	v_cmp_le_u32_e64 s[4:5], s14, v133
	v_cmp_le_u32_e64 s[6:7], s14, v134
	v_cmp_le_u32_e64 s[10:11], s14, v136
	v_cmp_le_u32_e64 s[26:27], s14, v137
	v_addc_co_u32_e64 v138, s[28:29], 0, v138, s[4:5]
	v_addc_co_u32_e64 v140, s[30:31], 0, v140, s[6:7]
	v_addc_co_u32_e64 v138, s[28:29], 0, v138, s[10:11]
	v_addc_co_u32_e64 v140, s[30:31], 0, v140, s[26:27]
	s_cmp_eq_u32 s32, 3
	s_cbranch_scc1 .Lsqb_red
	v_cmp_le_u32_e64 s[4:5], s14, v46
	v_cmp_le_u32_e64 s[6:7], s14, v48
	v_cmp_le_u32_e64 s[10:11], s14, v47
	v_cmp_le_u32_e64 s[26:27], s14, v49
	v_addc_co_u32_e64 v138, s[28:29], 0, v138, s[4:5]
	v_addc_co_u32_e64 v140, s[30:31], 0, v140, s[6:7]
	v_addc_co_u32_e64 v138, s[28:29], 0, v138, s[10:11]
	v_addc_co_u32_e64 v140, s[30:31], 0, v140, s[26:27]
	v_cmp_le_u32_e64 s[4:5], s14, v42
	v_cmp_le_u32_e64 s[6:7], s14, v50
	v_cmp_le_u32_e64 s[10:11], s14, v43
	v_cmp_le_u32_e64 s[26:27], s14, v44
	v_addc_co_u32_e64 v138, s[28:29], 0, v138, s[4:5]
	v_addc_co_u32_e64 v140, s[30:31], 0, v140, s[6:7]
	v_addc_co_u32_e64 v138, s[28:29], 0, v138, s[10:11]
	v_addc_co_u32_e64 v140, s[30:31], 0, v140, s[26:27]
	s_cmp_eq_u32 s32, 4
	s_cbranch_scc1 .Lsqb_red
	v_cmp_le_u32_e64 s[4:5], s14, v38
	v_cmp_le_u32_e64 s[6:7], s14, v45
	v_cmp_le_u32_e64 s[10:11], s14, v39
	v_cmp_le_u32_e64 s[26:27], s14, v40
	v_addc_co_u32_e64 v138, s[28:29], 0, v138, s[4:5]
	v_addc_co_u32_e64 v140, s[30:31], 0, v140, s[6:7]
	v_addc_co_u32_e64 v138, s[28:29], 0, v138, s[10:11]
	v_addc_co_u32_e64 v140, s[30:31], 0, v140, s[26:27]
	v_cmp_le_u32_e64 s[4:5], s14, v41
	v_cmp_le_u32_e64 s[6:7], s14, v52
	v_cmp_le_u32_e64 s[10:11], s14, v51
	v_cmp_le_u32_e64 s[26:27], s14, v54
	v_addc_co_u32_e64 v138, s[28:29], 0, v138, s[4:5]
	v_addc_co_u32_e64 v140, s[30:31], 0, v140, s[6:7]
	v_addc_co_u32_e64 v138, s[28:29], 0, v138, s[10:11]
	v_addc_co_u32_e64 v140, s[30:31], 0, v140, s[26:27]
	s_cmp_eq_u32 s32, 5
	s_cbranch_scc1 .Lsqb_red
	v_cmp_le_u32_e64 s[4:5], s14, v53
	v_cmp_le_u32_e64 s[6:7], s14, v56
	v_cmp_le_u32_e64 s[10:11], s14, v55
	v_cmp_le_u32_e64 s[26:27], s14, v57
	v_addc_co_u32_e64 v138, s[28:29], 0, v138, s[4:5]
	v_addc_co_u32_e64 v140, s[30:31], 0, v140, s[6:7]
	v_addc_co_u32_e64 v138, s[28:29], 0, v138, s[10:11]
	v_addc_co_u32_e64 v140, s[30:31], 0, v140, s[26:27]
	v_cmp_le_u32_e64 s[4:5], s14, v58
	v_cmp_le_u32_e64 s[6:7], s14, v60
	v_cmp_le_u32_e64 s[10:11], s14, v59
	v_cmp_le_u32_e64 s[26:27], s14, v61
	v_addc_co_u32_e64 v138, s[28:29], 0, v138, s[4:5]
	v_addc_co_u32_e64 v140, s[30:31], 0, v140, s[6:7]
	v_addc_co_u32_e64 v138, s[28:29], 0, v138, s[10:11]
	v_addc_co_u32_e64 v140, s[30:31], 0, v140, s[26:27]
	v_cmp_le_u32_e64 s[4:5], s14, v62
	v_cmp_le_u32_e64 s[6:7], s14, v64
	v_cmp_le_u32_e64 s[10:11], s14, v63
	v_cmp_le_u32_e64 s[26:27], s14, v65
	v_addc_co_u32_e64 v138, s[28:29], 0, v138, s[4:5]
	v_addc_co_u32_e64 v140, s[30:31], 0, v140, s[6:7]
	v_addc_co_u32_e64 v138, s[28:29], 0, v138, s[10:11]
	v_addc_co_u32_e64 v140, s[30:31], 0, v140, s[26:27]
	v_cmp_le_u32_e64 s[4:5], s14, v72
	v_cmp_le_u32_e64 s[6:7], s14, v73
	v_cmp_le_u32_e64 s[10:11], s14, v74
	v_cmp_le_u32_e64 s[26:27], s14, v75
	v_addc_co_u32_e64 v138, s[28:29], 0, v138, s[4:5]
	v_addc_co_u32_e64 v140, s[30:31], 0, v140, s[6:7]
	v_addc_co_u32_e64 v138, s[28:29], 0, v138, s[10:11]
	v_addc_co_u32_e64 v140, s[30:31], 0, v140, s[26:27]

; __device__ __forceinline__ float keyval(unsigned k) { return __uint_as_float((k & 0x80000000u) ? (k ^ 0x80000000u) : ~k); }
; __device__ __forceinline__ unsigned valkey(float f) { const unsigned b = __float_as_uint(f); return b ^ ((unsigned)((int)b >> 31) | 0x80000000u); }
; __device__ __forceinline__ void select_query(const unsigned (&u)[64], unsigned vmax, int q, int b, int lane, unsigned* MASKb) {
;     ...
;         while (!done) {
;             if (hi - lo <= 1u) { T = lo; exact = false; break; }
;             const float vlo = keyval(lo), vhi = keyval(hi);
;             const float frac = (it >= 9 && (it & 1)) ? 0.5f : Llo * __builtin_amdgcn_rcpf(Llo + Lhi);
;             unsigned mid = valkey(vlo + frac * (vhi - vlo));
;             if (mid <= lo) mid = lo + 1u;
;             if (mid >= hi) mid = hi - 1u;
.Lsqb_next:
	s_sub_u32 s26, s12, s13
	s_cmp_lt_u32 s26, 2
	s_cbranch_scc1 .Lsqb_collapse
	s_cmp_eq_u32 s101, 0
	s_cbranch_scc1 .Lsqb_lin
	s_cmp_lt_i32 s22, 9
	s_cbranch_scc0 .Lsqb_lin
	v_add_f32_e32 v142, v139, v141
	v_sub_f32_e32 v140, v77, v76
	v_rcp_f32_e32 v142, v142
	s_nop 0
	v_mul_f32_e32 v142, v139, v142
	v_fma_f32 v146, v142, v140, v76
	v_log_f32_e32 v138, v146
	s_nop 0
	v_mul_f32_e32 v138, 0x3f2aaaab, v138
	v_exp_f32_e32 v142, v138
	s_nop 0
	v_readfirstlane_b32 s14, v142
	s_bitset1_b32 s14, 31
	s_branch .Lsqb_clamp
